# grid barrier: non-leader workgroups poll TOPGEN directly (no XGEN relay)
# baseline (speedup 1.0000x reference)
.LBB0_73:
	s_or_b64 exec, exec, s[10:11]
	v_cvt_f32_u32_e32 v6, v4
	s_waitcnt vmcnt(0)
	v_readfirstlane_b32 s8, v5
	v_sub_u32_e32 v5, 0, v4
	v_rcp_iflag_f32_e32 v6, v6
	v_add_u32_e32 v7, s8, v3
	v_mul_f32_e32 v6, 0x4f7ffffe, v6
	v_cvt_u32_f32_e32 v6, v6
	v_mul_lo_u32 v3, v5, v6
	v_mul_hi_u32 v3, v6, v3
	v_add_u32_e32 v3, v6, v3
	v_mul_hi_u32 v3, v7, v3
	v_mul_lo_u32 v5, v3, v4
	v_sub_u32_e32 v5, v7, v5
	v_add_u32_e32 v6, 1, v3
	v_cmp_ge_u32_e32 vcc, v5, v4
	s_nop 1
	v_cndmask_b32_e32 v3, v3, v6, vcc
	v_sub_u32_e32 v6, v5, v4
	v_cndmask_b32_e32 v5, v5, v6, vcc
	v_add_u32_e32 v6, 1, v3
	v_cmp_ge_u32_e32 vcc, v5, v4
	v_add_u32_e32 v5, 1, v7
	s_nop 0
	v_cndmask_b32_e32 v3, v3, v6, vcc
	v_mul_lo_u32 v6, v4, v3
	v_add_u32_e32 v4, v6, v4
	v_cmp_ne_u32_e32 vcc, v5, v4
	s_and_saveexec_b64 s[8:9], vcc
	s_xor_b64 s[8:9], exec, s[8:9]
	s_cbranch_execz .LBB0_87
	s_waitcnt lgkmcnt(0)
	v_mov_b32_e32 v2, 0
	s_add_u32 s14, s76, 0xf46dd00
	s_addc_u32 s15, s77, 0
	global_load_dword v2, v2, s[14:15] sc1
	s_waitcnt vmcnt(0)
	v_cmp_eq_u32_e32 vcc, v2, v3
	s_and_saveexec_b64 s[10:11], vcc
	s_cbranch_execz .LBB0_86
	s_add_u32 s12, s76, 0xf46aa00
	s_addc_u32 s13, s77, 0
	s_mov_b32 s26, 1
	s_mov_b64 s[16:17], 0
	v_mov_b32_e32 v2, 0
	s_branch .LBB0_77

.LBB0_104:
	s_or_b64 exec, exec, s[8:9]
	s_mov_b64 s[8:9], exec
	v_mbcnt_lo_u32_b32 v2, s8, 0
	v_mbcnt_hi_u32_b32 v2, s9, v2
	v_cmp_eq_u32_e32 vcc, 0, v2
	s_waitcnt vmcnt(0)
	buffer_inv sc1
	s_and_saveexec_b64 s[10:11], vcc
	s_cbranch_execz .LBB0_106
	s_bcnt1_i32_b64 s8, s[8:9]
	v_mov_b32_e32 v2, 0x2000
	v_mov_b32_e32 v3, s8
.LBB0_106:
	s_or_b64 exec, exec, s[10:11]
	s_waitcnt vmcnt(0)

.LBB0_145:
	s_or_b64 exec, exec, s[6:7]
	v_cvt_f32_u32_e32 v6, v4
	s_waitcnt vmcnt(0)
	v_readfirstlane_b32 s4, v5
	v_sub_u32_e32 v5, 0, v4
	v_rcp_iflag_f32_e32 v6, v6
	v_add_u32_e32 v7, s4, v3
	v_mul_f32_e32 v6, 0x4f7ffffe, v6
	v_cvt_u32_f32_e32 v6, v6
	v_mul_lo_u32 v3, v5, v6
	v_mul_hi_u32 v3, v6, v3
	v_add_u32_e32 v3, v6, v3
	v_mul_hi_u32 v3, v7, v3
	v_mul_lo_u32 v5, v3, v4
	v_sub_u32_e32 v5, v7, v5
	v_add_u32_e32 v6, 1, v3
	v_cmp_ge_u32_e32 vcc, v5, v4
	s_nop 1
	v_cndmask_b32_e32 v3, v3, v6, vcc
	v_sub_u32_e32 v6, v5, v4
	v_cndmask_b32_e32 v5, v5, v6, vcc
	v_add_u32_e32 v6, 1, v3
	v_cmp_ge_u32_e32 vcc, v5, v4
	v_add_u32_e32 v5, 1, v7
	s_nop 0
	v_cndmask_b32_e32 v3, v3, v6, vcc
	v_mul_lo_u32 v6, v4, v3
	v_add_u32_e32 v4, v6, v4
	v_cmp_ne_u32_e32 vcc, v5, v4
	s_and_saveexec_b64 s[4:5], vcc
	s_xor_b64 s[4:5], exec, s[4:5]
	s_cbranch_execz .LBB0_159
	s_waitcnt lgkmcnt(0)
	v_mov_b32_e32 v2, 0
	s_add_u32 s10, s76, 0xf46dd00
	s_addc_u32 s11, s77, 0
	global_load_dword v2, v2, s[10:11] sc1
	s_waitcnt vmcnt(0)
	v_cmp_eq_u32_e32 vcc, v2, v3
	s_and_saveexec_b64 s[6:7], vcc
	s_cbranch_execz .LBB0_158
	s_add_u32 s8, s76, 0xf46aa00
	s_addc_u32 s9, s77, 0
	s_mov_b32 s22, 1
	s_mov_b64 s[12:13], 0
	v_mov_b32_e32 v2, 0
	s_branch .LBB0_149

.LBB0_176:
	s_or_b64 exec, exec, s[4:5]
	s_mov_b64 s[4:5], exec
	v_mbcnt_lo_u32_b32 v2, s4, 0
	v_mbcnt_hi_u32_b32 v2, s5, v2
	v_cmp_eq_u32_e32 vcc, 0, v2
	s_waitcnt vmcnt(0)
	buffer_inv sc1
	s_and_saveexec_b64 s[6:7], vcc
	s_cbranch_execz .LBB0_178
	s_bcnt1_i32_b64 s4, s[4:5]
	v_mov_b32_e32 v2, 0x2000
	v_mov_b32_e32 v3, s4
.LBB0_178:
	s_or_b64 exec, exec, s[6:7]
	s_waitcnt vmcnt(0)

.LBB0_414:
	s_or_b64 exec, exec, s[8:9]
	v_cvt_f32_u32_e32 v6, v4
	s_waitcnt vmcnt(0)
	v_readfirstlane_b32 s6, v5
	v_sub_u32_e32 v5, 0, v4
	v_rcp_iflag_f32_e32 v6, v6
	v_add_u32_e32 v7, s6, v3
	v_mul_f32_e32 v6, 0x4f7ffffe, v6
	v_cvt_u32_f32_e32 v6, v6
	v_mul_lo_u32 v3, v5, v6
	v_mul_hi_u32 v3, v6, v3
	v_add_u32_e32 v3, v6, v3
	v_mul_hi_u32 v3, v7, v3
	v_mul_lo_u32 v5, v3, v4
	v_sub_u32_e32 v5, v7, v5
	v_add_u32_e32 v6, 1, v3
	v_cmp_ge_u32_e32 vcc, v5, v4
	s_nop 1
	v_cndmask_b32_e32 v3, v3, v6, vcc
	v_sub_u32_e32 v6, v5, v4
	v_cndmask_b32_e32 v5, v5, v6, vcc
	v_add_u32_e32 v6, 1, v3
	v_cmp_ge_u32_e32 vcc, v5, v4
	v_add_u32_e32 v5, 1, v7
	s_nop 0
	v_cndmask_b32_e32 v3, v3, v6, vcc
	v_mul_lo_u32 v6, v4, v3
	v_add_u32_e32 v4, v6, v4
	v_cmp_ne_u32_e32 vcc, v5, v4
	s_and_saveexec_b64 s[6:7], vcc
	s_xor_b64 s[6:7], exec, s[6:7]
	s_cbranch_execz .LBB0_428
	s_waitcnt lgkmcnt(0)
	v_mov_b32_e32 v2, 0
	s_add_u32 s12, s76, 0xf46dd00
	s_addc_u32 s13, s77, 0
	global_load_dword v2, v2, s[12:13] sc1
	s_waitcnt vmcnt(0)
	v_cmp_eq_u32_e32 vcc, v2, v3
	s_and_saveexec_b64 s[8:9], vcc
	s_cbranch_execz .LBB0_427
	s_add_u32 s10, s76, 0xf46aa00
	s_addc_u32 s11, s77, 0
	s_mov_b32 s24, 1
	s_mov_b64 s[14:15], 0
	v_mov_b32_e32 v2, 0
	s_branch .LBB0_418

.LBB0_445:
	s_or_b64 exec, exec, s[6:7]
	s_mov_b64 s[6:7], exec
	v_mbcnt_lo_u32_b32 v2, s6, 0
	v_mbcnt_hi_u32_b32 v2, s7, v2
	v_cmp_eq_u32_e32 vcc, 0, v2
	s_waitcnt vmcnt(0)
	buffer_inv sc1
	s_and_saveexec_b64 s[8:9], vcc
	s_cbranch_execz .LBB0_447
	s_bcnt1_i32_b64 s6, s[6:7]
	v_mov_b32_e32 v2, 0x2000
	v_mov_b32_e32 v3, s6
.LBB0_447:
	s_or_b64 exec, exec, s[8:9]
	s_waitcnt vmcnt(0)

.LBB0_524:
	s_or_b64 exec, exec, s[8:9]
	s_mov_b64 s[8:9], exec
	v_mbcnt_lo_u32_b32 v2, s8, 0
	v_mbcnt_hi_u32_b32 v2, s9, v2
	v_cmp_eq_u32_e32 vcc, 0, v2
	s_waitcnt vmcnt(0)
	buffer_inv sc1
	s_and_saveexec_b64 s[10:11], vcc
	s_cbranch_execz .LBB0_526
	s_bcnt1_i32_b64 s8, s[8:9]
	v_mov_b32_e32 v2, 0x2000
	v_mov_b32_e32 v3, s8
.LBB0_526:
	s_or_b64 exec, exec, s[10:11]
	s_waitcnt vmcnt(0)

.LBB0_597:
	s_or_b64 exec, exec, s[8:9]
	s_mov_b64 s[8:9], exec
	v_mbcnt_lo_u32_b32 v2, s8, 0
	v_mbcnt_hi_u32_b32 v2, s9, v2
	v_cmp_eq_u32_e32 vcc, 0, v2
	s_waitcnt vmcnt(0)
	buffer_inv sc1
	s_and_saveexec_b64 s[10:11], vcc
	s_cbranch_execz .LBB0_599
	s_bcnt1_i32_b64 s8, s[8:9]
	v_mov_b32_e32 v2, 0x2000
	v_mov_b32_e32 v3, s8
.LBB0_599:
	s_or_b64 exec, exec, s[10:11]
	s_waitcnt vmcnt(0)

.LBB0_661:
	s_or_b64 exec, exec, s[16:17]
	v_cvt_f32_u32_e32 v6, v4
	s_waitcnt vmcnt(0)
	v_readfirstlane_b32 s14, v5
	v_sub_u32_e32 v5, 0, v4
	v_rcp_iflag_f32_e32 v6, v6
	v_add_u32_e32 v7, s14, v3
	v_mul_f32_e32 v6, 0x4f7ffffe, v6
	v_cvt_u32_f32_e32 v6, v6
	v_mul_lo_u32 v3, v5, v6
	v_mul_hi_u32 v3, v6, v3
	v_add_u32_e32 v3, v6, v3
	v_mul_hi_u32 v3, v7, v3
	v_mul_lo_u32 v5, v3, v4
	v_sub_u32_e32 v5, v7, v5
	v_add_u32_e32 v6, 1, v3
	v_cmp_ge_u32_e32 vcc, v5, v4
	s_nop 1
	v_cndmask_b32_e32 v3, v3, v6, vcc
	v_sub_u32_e32 v6, v5, v4
	v_cndmask_b32_e32 v5, v5, v6, vcc
	v_add_u32_e32 v6, 1, v3
	v_cmp_ge_u32_e32 vcc, v5, v4
	v_add_u32_e32 v5, 1, v7
	s_nop 0
	v_cndmask_b32_e32 v3, v3, v6, vcc
	v_mul_lo_u32 v6, v4, v3
	v_add_u32_e32 v4, v6, v4
	v_cmp_ne_u32_e32 vcc, v5, v4
	s_and_saveexec_b64 s[14:15], vcc
	s_xor_b64 s[14:15], exec, s[14:15]
	s_cbranch_execz .LBB0_675
	s_waitcnt lgkmcnt(0)
	v_mov_b32_e32 v2, 0
	s_add_u32 s20, s76, 0xf46dd00
	s_addc_u32 s21, s77, 0
	global_load_dword v2, v2, s[20:21] sc1
	s_waitcnt vmcnt(0)
	v_cmp_eq_u32_e32 vcc, v2, v3
	s_and_saveexec_b64 s[16:17], vcc
	s_cbranch_execz .LBB0_674
	s_add_u32 s18, s76, 0xf46aa00
	s_addc_u32 s19, s77, 0
	s_mov_b32 s33, 1
	s_mov_b64 s[22:23], 0
	v_mov_b32_e32 v2, 0
	s_branch .LBB0_665

.LBB0_692:
	s_or_b64 exec, exec, s[14:15]
	s_mov_b64 s[14:15], exec
	v_mbcnt_lo_u32_b32 v2, s14, 0
	v_mbcnt_hi_u32_b32 v2, s15, v2
	v_cmp_eq_u32_e32 vcc, 0, v2
	s_waitcnt vmcnt(0)
	buffer_inv sc1
	s_and_saveexec_b64 s[16:17], vcc
	s_cbranch_execz .LBB0_694
	s_bcnt1_i32_b64 s14, s[14:15]
	v_mov_b32_e32 v2, 0x2000
	v_mov_b32_e32 v3, s14
.LBB0_694:
	s_or_b64 exec, exec, s[16:17]
	s_waitcnt vmcnt(0)

.LBB0_756:
	s_or_b64 exec, exec, s[8:9]
	v_cvt_f32_u32_e32 v5, v3
	s_waitcnt vmcnt(0)
	v_readfirstlane_b32 s4, v4
	v_sub_u32_e32 v4, 0, v3
	v_rcp_iflag_f32_e32 v5, v5
	v_add_u32_e32 v6, s4, v2
	v_mul_f32_e32 v5, 0x4f7ffffe, v5
	v_cvt_u32_f32_e32 v5, v5
	v_mul_lo_u32 v2, v4, v5
	v_mul_hi_u32 v2, v5, v2
	v_add_u32_e32 v2, v5, v2
	v_mul_hi_u32 v2, v6, v2
	v_mul_lo_u32 v4, v2, v3
	v_sub_u32_e32 v4, v6, v4
	v_add_u32_e32 v5, 1, v2
	v_cmp_ge_u32_e32 vcc, v4, v3
	s_nop 1
	v_cndmask_b32_e32 v2, v2, v5, vcc
	v_sub_u32_e32 v5, v4, v3
	v_cndmask_b32_e32 v4, v4, v5, vcc
	v_add_u32_e32 v5, 1, v2
	v_cmp_ge_u32_e32 vcc, v4, v3
	v_add_u32_e32 v4, 1, v6
	s_nop 0
	v_cndmask_b32_e32 v2, v2, v5, vcc
	v_mul_lo_u32 v5, v3, v2
	v_add_u32_e32 v3, v5, v3
	v_cmp_ne_u32_e32 vcc, v4, v3
	s_and_saveexec_b64 s[4:5], vcc
	s_xor_b64 s[4:5], exec, s[4:5]
	s_cbranch_execz .LBB0_770
	s_waitcnt lgkmcnt(0)
	v_mov_b32_e32 v1, 0
	s_add_u32 s12, s76, 0xf46dd00
	s_addc_u32 s13, s77, 0
	global_load_dword v1, v1, s[12:13] sc1
	s_waitcnt vmcnt(0)
	v_cmp_eq_u32_e32 vcc, v1, v2
	s_and_saveexec_b64 s[8:9], vcc
	s_cbranch_execz .LBB0_769
	s_add_u32 s10, s76, 0xf46aa00
	s_addc_u32 s11, s77, 0
	s_mov_b32 s24, 1
	s_mov_b64 s[14:15], 0
	v_mov_b32_e32 v1, 0
	s_branch .LBB0_760

.LBB0_787:
	s_or_b64 exec, exec, s[4:5]
	s_mov_b64 s[4:5], exec
	v_mbcnt_lo_u32_b32 v1, s4, 0
	v_mbcnt_hi_u32_b32 v1, s5, v1
	v_cmp_eq_u32_e32 vcc, 0, v1
	s_waitcnt vmcnt(0)
	buffer_inv sc1
	s_and_saveexec_b64 s[8:9], vcc
	s_cbranch_execz .LBB0_789
	s_bcnt1_i32_b64 s4, s[4:5]
	v_mov_b32_e32 v1, 0x2000
	v_mov_b32_e32 v2, s4
.LBB0_789:
	s_or_b64 exec, exec, s[8:9]
	s_waitcnt vmcnt(0)
